# GLA chunk-summary units of the 5th round remapped from workgroups 0-63 to 192-255 (fewer E1 rows there)
# baseline (speedup 1.0000x reference)
; #define LAS __attribute__((address_space(3)))
; __device__ __forceinline__ unsigned short f2bf(float f) { return (unsigned short)(cvt_pk_bf16(f, 0.f) & 0xffffu); }
; __device__ __forceinline__ void gla_p1(CArgs& a, int l, int cc, int h, LAS float* L, int dup, bool stagew) {
;     ...
;         oqf[dd] = q * __expf(cf); oqb[dd] = q * __expf(cb); okf[dd] = k * __expf(-cf); okb[dd] = k * __expf(-cb);
;         *(LAS unsigned short*)(B + GB_QDF + (d * HS + lane) * 2) = f2bf(k * __expf(totf - cf));
;         *(LAS unsigned short*)(B + GB_QDB + (d * HS + lane) * 2) = f2bf(k * __expf(totb - cb));
;         if (lane == 0) { DEC[(size_t)slot * 64 + d] = __expf(totf); DEC[(size_t)(slot + 1) * 64 + d] = __expf(totb); } }
;     { u32x4 w;
;       w.x = cvt_pk_bf16(oqf[0], oqf[1]); w.y = cvt_pk_bf16(oqf[2], oqf[3]); w.z = cvt_pk_bf16(oqf[4], oqf[5]); w.w = cvt_pk_bf16(oqf[6], oqf[7]); *(u32x4*)(GQ + 0 * 4096 + lane * 64 + 8 * wid) = w;
;       w.x = cvt_pk_bf16(oqb[0], oqb[1]); w.y = cvt_pk_bf16(oqb[2], oqb[3]); w.z = cvt_pk_bf16(oqb[4], oqb[5]); w.w = cvt_pk_bf16(oqb[6], oqb[7]); *(u32x4*)(GQ + 1 * 4096 + lane * 64 + 8 * wid) = w;
;       w.x = cvt_pk_bf16(okf[0], okf[1]); w.y = cvt_pk_bf16(okf[2], okf[3]); w.z = cvt_pk_bf16(okf[4], okf[5]); w.w = cvt_pk_bf16(okf[6], okf[7]); *(u32x4*)(GQ + 2 * 4096 + lane * 64 + 8 * wid) = w;
;       w.x = cvt_pk_bf16(okb[0], okb[1]); w.y = cvt_pk_bf16(okb[2], okb[3]); w.z = cvt_pk_bf16(okb[4], okb[5]); w.w = cvt_pk_bf16(okb[6], okb[7]); *(u32x4*)(GQ + 3 * 4096 + lane * 64 + 8 * wid) = w; }
;     if (PROBE_CUT == 2 && dup) return;
;     __syncthreads();
;     { const int r32 = lane & 31, hi = lane >> 5, dir = wid >> 2, eb = wid & 3;
;       const LAS unsigned char* X = B + GB_VT; const LAS unsigned char* Y = B + (dir ? GB_QDB : GB_QDF);
;       f32x16 c0 = {}, c1 = {};
; #pragma unroll
;       for (int ks = 0; ks < 4; ++ks) { const bf16x8 av = ldfrag(X, 32 * eb + r32, ks, hi), b0 = ldfrag(Y, r32, ks, hi), b1 = ldfrag(Y, 32 + r32, ks, hi);
;           c0 = __builtin_amdgcn_mfma_f32_32x32x16_bf16(av, b0, c0, 0, 0, 0); c1 = __builtin_amdgcn_mfma_f32_32x32x16_bf16(av, b1, c1, 0, 0, 0); }
;       float* out = KVS + (size_t)(slot + dir) * 8192;
; #pragma unroll
;       for (int r = 0; r < 16; ++r) { const int e = 32 * eb + crow16(r, hi); out[e * 64 + r32] = c0[r]; out[e * 64 + 32 + r32] = c1[r]; } }
.LBB0_132:
	s_or_b64 exec, exec, s[14:15]
	v_mul_f32_e32 v15, 0xbfb8aa3b, v14
	v_mul_f32_e32 v16, 0xbfb8aa3b, v13
	v_exp_f32_e32 v15, v15
	v_exp_f32_e32 v16, v16
	v_mul_f32_e32 v13, 0x3fb8aa3b, v13
	v_mul_f32_e32 v17, 0xbfb8aa3b, v69
	v_mul_f32_e32 v15, v15, v9
	v_mul_f32_e32 v16, v16, v9
	v_mul_f32_e32 v9, 0x3fb8aa3b, v14
	v_mul_f32_e32 v18, 0xbfb8aa3b, v68
	v_exp_f32_e32 v9, v9
	v_exp_f32_e32 v13, v13
	v_exp_f32_e32 v17, v17
	v_exp_f32_e32 v18, v18
	v_and_b32_e32 v14, 0xffff0000, v5
	v_mul_f32_e32 v14, 0x3e000000, v14
	v_mul_f32_e32 v19, v14, v9
	v_mul_f32_e32 v9, v14, v13
	v_mul_f32_e32 v13, v17, v70
	v_mul_f32_e32 v14, v18, v70
	v_mul_f32_e32 v17, 0x3fb8aa3b, v69
	v_mul_f32_e32 v18, 0x3fb8aa3b, v68
	v_mul_f32_e32 v20, 0xbfb8aa3b, v67
	v_mul_f32_e32 v21, 0xbfb8aa3b, v66
	v_exp_f32_e32 v17, v17
	v_exp_f32_e32 v18, v18
	v_exp_f32_e32 v20, v20
	v_exp_f32_e32 v21, v21
	v_lshlrev_b32_e32 v5, 16, v5
	v_mul_f32_e32 v5, 0x3e000000, v5
	v_mul_f32_e32 v17, v5, v17
	v_mul_f32_e32 v5, v5, v18
	v_mul_f32_e32 v18, v20, v8
	v_mul_f32_e32 v20, v21, v8
	v_mul_f32_e32 v8, 0x3fb8aa3b, v67
	v_mul_f32_e32 v24, 0x3fb8aa3b, v66
	v_mul_f32_e32 v25, 0xbfb8aa3b, v64
	v_mul_f32_e32 v26, 0xbfb8aa3b, v63
	v_exp_f32_e32 v8, v8
	v_exp_f32_e32 v24, v24
	v_exp_f32_e32 v25, v25
	v_exp_f32_e32 v26, v26
	v_and_b32_e32 v21, 0xffff0000, v4
	v_mul_f32_e32 v21, 0x3e000000, v21
	v_mul_f32_e32 v27, v21, v8
	v_mul_f32_e32 v8, v21, v24
	v_mul_f32_e32 v21, v25, v65
	v_mul_f32_e32 v24, v26, v65
	v_mul_f32_e32 v25, 0x3fb8aa3b, v64
	v_mul_f32_e32 v26, 0x3fb8aa3b, v63
	v_mul_f32_e32 v28, 0xbfb8aa3b, v61
	v_mul_f32_e32 v29, 0xbfb8aa3b, v60
	v_exp_f32_e32 v25, v25
	v_exp_f32_e32 v26, v26
	v_exp_f32_e32 v28, v28
	v_exp_f32_e32 v29, v29
	v_lshlrev_b32_e32 v4, 16, v4
	v_mul_f32_e32 v4, 0x3e000000, v4
	v_mul_f32_e32 v25, v4, v25
	v_mul_f32_e32 v4, v4, v26
	v_mul_f32_e32 v26, v28, v62
	v_mul_f32_e32 v28, v29, v62
	v_mul_f32_e32 v29, 0x3fb8aa3b, v61
	v_mul_f32_e32 v31, 0x3fb8aa3b, v60
	v_mul_f32_e32 v32, 0xbfb8aa3b, v58
	v_mul_f32_e32 v33, 0xbfb8aa3b, v57
	v_exp_f32_e32 v29, v29
	v_exp_f32_e32 v31, v31
	v_exp_f32_e32 v32, v32
	v_exp_f32_e32 v33, v33
	v_and_b32_e32 v30, 0xffff0000, v3
	v_mul_f32_e32 v30, 0x3e000000, v30
	v_mul_f32_e32 v29, v30, v29
	v_mul_f32_e32 v30, v30, v31
	v_mul_f32_e32 v31, v32, v59
	v_mul_f32_e32 v32, v33, v59
	v_mul_f32_e32 v33, 0x3fb8aa3b, v58
	v_mul_f32_e32 v34, 0x3fb8aa3b, v57
	v_mul_f32_e32 v35, 0xbfb8aa3b, v55
	v_mul_f32_e32 v36, 0xbfb8aa3b, v54
	v_exp_f32_e32 v33, v33
	v_exp_f32_e32 v34, v34
	v_exp_f32_e32 v35, v35
	v_exp_f32_e32 v36, v36
	v_lshlrev_b32_e32 v3, 16, v3
	v_mul_f32_e32 v3, 0x3e000000, v3
	v_mul_f32_e32 v39, 0xbfb8aa3b, v11
	v_mul_f32_e32 v40, 0xbfb8aa3b, v10
	v_mul_f32_e32 v11, 0x3fb8aa3b, v11
	v_mul_f32_e32 v10, 0x3fb8aa3b, v10
	v_mul_f32_e32 v33, v3, v33
	v_mul_f32_e32 v3, v3, v34
	v_mul_f32_e32 v34, v35, v56
	v_mul_f32_e32 v35, v36, v56
	v_mul_f32_e32 v36, 0x3fb8aa3b, v55
	v_mul_f32_e32 v38, 0x3fb8aa3b, v54
	v_exp_f32_e32 v11, v11
	v_exp_f32_e32 v10, v10
	v_exp_f32_e32 v36, v36
	v_exp_f32_e32 v38, v38
	s_ashr_i32 s51, s50, 31
	v_and_b32_e32 v37, 0xffff0000, v2
	v_lshlrev_b32_e32 v2, 16, v2
	s_lshl_b64 s[4:5], s[50:51], 15
	v_mul_f32_e32 v2, 0x3e000000, v2
	s_add_u32 s4, s8, s4
	v_mul_f32_e32 v37, 0x3e000000, v37
	v_mul_f32_e32 v11, v2, v11
	v_mul_f32_e32 v2, v2, v10
	s_addc_u32 s5, s9, s5
	v_lshlrev_b32_e32 v0, 1, v0
	v_mul_f32_e32 v36, v37, v36
	v_mul_f32_e32 v37, v37, v38
	v_cvt_pk_bf16_f32 v2, v2, v37
	v_cvt_pk_bf16_f32 v3, v3, v30
	v_cvt_pk_bf16_f32 v4, v4, v8
	v_cvt_pk_bf16_f32 v5, v5, v9
	v_lshl_add_u64 v[8:9], s[4:5], 0, v[0:1]
	v_lshl_add_u64 v[6:7], v[6:7], 1, v[8:9]
	s_movk_i32 s4, 0x2000
	v_exp_f32_e32 v39, v39
	v_exp_f32_e32 v40, v40
	v_add_co_u32_e32 v8, vcc, s4, v6
	s_movk_i32 s4, 0x4000
	s_nop 0
	v_addc_co_u32_e32 v9, vcc, 0, v7, vcc
	global_store_dwordx4 v[6:7], v[2:5], off
	v_mul_f32_e32 v38, v39, v12
	v_mul_f32_e32 v12, v40, v12
	v_cvt_pk_bf16_f32 v2, v11, v36
	v_cvt_pk_bf16_f32 v3, v33, v29
	v_cvt_pk_bf16_f32 v4, v25, v27
	v_cvt_pk_bf16_f32 v5, v17, v19
	global_store_dwordx4 v[8:9], v[2:5], off
	v_add_co_u32_e32 v8, vcc, s4, v6
	s_movk_i32 s4, 0x6000
	s_nop 0
	v_addc_co_u32_e32 v9, vcc, 0, v7, vcc
	v_cvt_pk_bf16_f32 v2, v12, v35
	v_add_co_u32_e32 v6, vcc, s4, v6
	v_cvt_pk_bf16_f32 v3, v32, v28
	v_cvt_pk_bf16_f32 v4, v24, v20
	v_cvt_pk_bf16_f32 v5, v14, v16
	global_store_dwordx4 v[8:9], v[2:5], off
	s_nop 0
	v_addc_co_u32_e32 v7, vcc, 0, v7, vcc
	v_cvt_pk_bf16_f32 v2, v38, v34
	v_and_b32_e32 v0, 31, v23
	s_bfe_u32 s6, s91, 0x20006
	v_cvt_pk_bf16_f32 v3, v31, v26
	v_cvt_pk_bf16_f32 v4, v21, v18
	v_cvt_pk_bf16_f32 v5, v13, v15
	global_store_dwordx4 v[6:7], v[2:5], off
	v_lshrrev_b32_e32 v42, 5, v22
	s_waitcnt lgkmcnt(0)
	v_lshl_or_b32 v2, s6, 5, v0
	v_mul_u32_u24_e32 v2, 0x90, v2
	v_lshlrev_b32_e32 v3, 4, v42
	v_add3_u32 v43, s17, v2, v3
	s_barrier
	s_cmpk_lt_u32 s91, 0x100
	s_mov_b32 s4, 0x8200
	ds_read_b128 v[18:21], v43
	s_cselect_b32 s4, s4, 0xa600
	s_add_i32 s4, s4, 0
	v_mul_u32_u24_e32 v2, 0x90, v0
	v_add3_u32 v44, s4, v2, v3
	ds_read_b128 v[2:5], v44
	s_waitcnt lgkmcnt(0)
	v_mfma_f32_32x32x16_bf16 v[2:17], v[18:21], v[2:5], 0
	ds_read_b128 v[22:25], v44 offset:4608
	ds_read_b128 v[34:37], v43 offset:32
	ds_read_b128 v[38:41], v44 offset:32
	s_ashr_i32 s4, s91, 8
	s_add_i32 s4, s4, s20
	s_ashr_i32 s5, s4, 31
	s_lshl_b64 s[4:5], s[4:5], 15
	s_add_u32 s4, s69, s4
	s_waitcnt lgkmcnt(2)
	v_mfma_f32_32x32x16_bf16 v[18:33], v[18:21], v[22:25], 0
	s_addc_u32 s5, s70, s5
	s_lshl_b32 s6, s6, 11
	s_add_i32 s50, s50, s64
	s_cmpk_lt_i32 s50, 0x400
	s_cbranch_scc1 .Lp1_cmp
	s_sub_i32 s50, s50, 0xc0
	s_cmpk_lt_i32 s50, 0x400
	s_cbranch_scc0 .Lp1_cmp
	s_movk_i32 s50, 0x7fff
; #define LAS __attribute__((address_space(3)))
; __device__ __forceinline__ int crow16(int r, int hi) { return (r & 3) + 8 * (r >> 2) + 4 * hi; }
; __device__ __forceinline__ void gla_p1(CArgs& a, int l, int cc, int h, LAS float* L, int dup, bool stagew) {
;     ...
;     { const int r32 = lane & 31, hi = lane >> 5, dir = wid >> 2, eb = wid & 3;
;       const LAS unsigned char* X = B + GB_VT; const LAS unsigned char* Y = B + (dir ? GB_QDB : GB_QDF);
;       f32x16 c0 = {}, c1 = {};
; #pragma unroll
;       for (int ks = 0; ks < 4; ++ks) { const bf16x8 av = ldfrag(X, 32 * eb + r32, ks, hi), b0 = ldfrag(Y, r32, ks, hi), b1 = ldfrag(Y, 32 + r32, ks, hi);
;           c0 = __builtin_amdgcn_mfma_f32_32x32x16_bf16(av, b0, c0, 0, 0, 0); c1 = __builtin_amdgcn_mfma_f32_32x32x16_bf16(av, b1, c1, 0, 0, 0); }
;       float* out = KVS + (size_t)(slot + dir) * 8192;
; #pragma unroll
;       for (int r = 0; r < 16; ++r) { const int e = 32 * eb + crow16(r, hi); out[e * 64 + r32] = c0[r]; out[e * 64 + 32 + r32] = c1[r]; } }
; __device__ __forceinline__ void run_phase(CArgs& a, int ph, unsigned char* lds_g, LAS unsigned char* lds, int dup) {
;     ...
;         if (!(dup && PROBE_DUP == 20)) { int hst = -1; for (int u = blockIdx.x; u < NCHUNK * 4; u += G) { const int h = u & 3; gla_p1(a, l, u >> 2, h, (LAS float*)lds, dup, h != hst); hst = h; } }
.Lp1_cmp:
	s_cmpk_gt_i32 s50, 0x43f
	s_waitcnt lgkmcnt(0)
	v_mfma_f32_32x32x16_bf16 v[2:17], v[34:37], v[38:41], v[2:17]
	ds_read_b128 v[38:41], v44 offset:4640
	s_waitcnt lgkmcnt(0)
	v_mfma_f32_32x32x16_bf16 v[18:33], v[34:37], v[38:41], v[18:33]
	ds_read_b128 v[34:37], v43 offset:64
	ds_read_b128 v[38:41], v44 offset:64
	s_waitcnt lgkmcnt(0)
	v_mfma_f32_32x32x16_bf16 v[2:17], v[34:37], v[38:41], v[2:17]
	ds_read_b128 v[38:41], v44 offset:4672
	s_waitcnt lgkmcnt(0)
	v_mfma_f32_32x32x16_bf16 v[18:33], v[34:37], v[38:41], v[18:33]
	ds_read_b128 v[34:37], v43 offset:96
	ds_read_b128 v[38:41], v44 offset:96
	s_waitcnt lgkmcnt(0)
	v_mfma_f32_32x32x16_bf16 v[2:17], v[34:37], v[38:41], v[2:17]
	ds_read_b128 v[38:41], v44 offset:4704
	s_waitcnt lgkmcnt(0)
	v_mfma_f32_32x32x16_bf16 v[18:33], v[34:37], v[38:41], v[18:33]
	v_lshlrev_b32_e32 v34, 8, v42
	v_or3_b32 v0, s6, v34, v0
	v_lshlrev_b32_e32 v0, 2, v0
	v_lshl_add_u64 v[34:35], s[4:5], 0, v[0:1]
	s_nop 4
	global_store_dword v0, v2, s[4:5]
	s_nop 1
	global_store_dword v0, v18, s[4:5] offset:128
	global_store_dword v0, v3, s[4:5] offset:256
	global_store_dword v0, v19, s[4:5] offset:384
	global_store_dword v0, v4, s[4:5] offset:512
	global_store_dword v0, v20, s[4:5] offset:640
	global_store_dword v0, v5, s[4:5] offset:768
	global_store_dword v0, v21, s[4:5] offset:896
	global_store_dword v0, v6, s[4:5] offset:2048
	global_store_dword v0, v22, s[4:5] offset:2176
	global_store_dword v0, v7, s[4:5] offset:2304
	global_store_dword v0, v23, s[4:5] offset:2432
	global_store_dword v0, v8, s[4:5] offset:2560
	global_store_dword v0, v24, s[4:5] offset:2688
	global_store_dword v0, v9, s[4:5] offset:2816
	global_store_dword v0, v25, s[4:5] offset:2944
	v_add_co_u32_e32 v2, vcc, s10, v34
	s_mov_b32 s4, s71
	s_nop 0
	v_addc_co_u32_e32 v3, vcc, 0, v35, vcc
	global_store_dword v[2:3], v10, off
	global_store_dword v[2:3], v26, off offset:128
	global_store_dword v[2:3], v11, off offset:256
	global_store_dword v[2:3], v27, off offset:384
	global_store_dword v[2:3], v12, off offset:512
	global_store_dword v[2:3], v28, off offset:640
	global_store_dword v[2:3], v13, off offset:768
	global_store_dword v[2:3], v29, off offset:896
	global_store_dword v[2:3], v14, off offset:2048
	global_store_dword v[2:3], v30, off offset:2176
	global_store_dword v[2:3], v15, off offset:2304
	global_store_dword v[2:3], v31, off offset:2432
	global_store_dword v[2:3], v16, off offset:2560
	global_store_dword v[2:3], v32, off offset:2688
	global_store_dword v[2:3], v17, off offset:2816
	global_store_dword v[2:3], v33, off offset:2944
	s_cbranch_scc1 .LBB0_160
